# v27: attention loop: one LDS wait per 4 MFMAs, slot-rotation SALU spread over the K.Q gaps, common case falls through with one test
# speedup vs baseline: 1.0622x; 1.0035x over previous
.Lat_loop:
	v_add_u32_e32 v188, s12, v157
	v_add_u32_e32 v189, s12, v158
	v_add_u32_e32 v222, s12, v159
	v_add_u32_e32 v223, s12, v160
	s_cmp_ge_i32 s5, s81
	s_cbranch_scc1 .Lat_rare_8
	s_waitcnt lgkmcnt(8)
	v_mfma_f32_32x32x16_bf16 v[0:15], v[224:227], v[114:117], v[0:15]
	v_exp_f32_e32 v82, v82
	v_exp_f32_e32 v83, v83
	ds_read_b64_tr_b16 v[224:225], v215 offset:8192
	ds_read_b64_tr_b16 v[226:227], v215 offset:10240
	v_mfma_f32_32x32x16_bf16 v[16:31], v[228:231], v[114:117], v[16:31]
	v_exp_f32_e32 v84, v84
	v_exp_f32_e32 v85, v85
	v_add_f32_e32 v180, v82, v83
	ds_read_b64_tr_b16 v[228:229], v165 offset:8192
	ds_read_b64_tr_b16 v[230:231], v165 offset:10240
	v_mfma_f32_32x32x16_bf16 v[32:47], v[232:235], v[114:117], v[32:47]
	v_exp_f32_e32 v86, v86
	v_exp_f32_e32 v87, v87
	v_add_f32_e32 v180, v180, v84
	v_add_f32_e32 v180, v180, v85
	ds_read_b64_tr_b16 v[232:233], v216 offset:8192
	ds_read_b64_tr_b16 v[234:235], v216 offset:10240
	v_mfma_f32_32x32x16_bf16 v[48:63], v[236:239], v[114:117], v[48:63]
	v_exp_f32_e32 v88, v88
	v_exp_f32_e32 v89, v89
	v_add_f32_e32 v180, v180, v86
	v_add_f32_e32 v180, v180, v87
	ds_read_b64_tr_b16 v[236:237], v217 offset:8192
	ds_read_b64_tr_b16 v[238:239], v217 offset:10240
	s_waitcnt lgkmcnt(8)
	v_mfma_f32_32x32x16_bf16 v[0:15], v[240:243], v[118:121], v[0:15]
	v_exp_f32_e32 v90, v90
	v_exp_f32_e32 v91, v91
	v_add_f32_e32 v180, v180, v88
	v_cvt_pk_bf16_f32 v114, v82, v83
	ds_read_b64_tr_b16 v[240:241], v215 offset:12288
	ds_read_b64_tr_b16 v[242:243], v215 offset:14336
	v_mfma_f32_32x32x16_bf16 v[16:31], v[130:133], v[118:121], v[16:31]
	v_exp_f32_e32 v92, v92
	v_exp_f32_e32 v93, v93
	v_add_f32_e32 v180, v180, v89
	v_cvt_pk_bf16_f32 v115, v84, v85
	ds_read_b64_tr_b16 v[130:131], v165 offset:12288
	ds_read_b64_tr_b16 v[132:133], v165 offset:14336
	v_mfma_f32_32x32x16_bf16 v[32:47], v[134:137], v[118:121], v[32:47]
	v_exp_f32_e32 v94, v94
	v_exp_f32_e32 v95, v95
	v_add_f32_e32 v180, v180, v90
	v_cvt_pk_bf16_f32 v116, v86, v87
	ds_read_b64_tr_b16 v[134:135], v216 offset:12288
	ds_read_b64_tr_b16 v[136:137], v216 offset:14336
	v_mfma_f32_32x32x16_bf16 v[48:63], v[184:187], v[118:121], v[48:63]
	v_exp_f32_e32 v96, v96
	v_exp_f32_e32 v97, v97
	v_add_f32_e32 v180, v180, v91
	v_cvt_pk_bf16_f32 v117, v88, v89
	ds_read_b64_tr_b16 v[184:185], v217 offset:12288
	ds_read_b64_tr_b16 v[186:187], v217 offset:14336
	s_waitcnt lgkmcnt(8)
	v_mfma_f32_32x32x16_bf16 v[0:15], v[224:227], v[122:125], v[0:15]
	v_exp_f32_e32 v98, v98
	v_exp_f32_e32 v99, v99
	v_add_f32_e32 v180, v180, v92
	v_cvt_pk_bf16_f32 v118, v90, v91
	v_mfma_f32_32x32x16_bf16 v[16:31], v[228:231], v[122:125], v[16:31]
	v_exp_f32_e32 v100, v100
	v_exp_f32_e32 v101, v101
	v_add_f32_e32 v180, v180, v93
	v_cvt_pk_bf16_f32 v119, v92, v93
	v_mfma_f32_32x32x16_bf16 v[32:47], v[232:235], v[122:125], v[32:47]
	v_exp_f32_e32 v102, v102
	v_exp_f32_e32 v103, v103
	v_add_f32_e32 v180, v180, v94
	v_cvt_pk_bf16_f32 v120, v94, v95
	v_mfma_f32_32x32x16_bf16 v[48:63], v[236:239], v[122:125], v[48:63]
	v_exp_f32_e32 v104, v104
	v_exp_f32_e32 v105, v105
	v_add_f32_e32 v180, v180, v95
	v_cvt_pk_bf16_f32 v121, v96, v97
	ds_read_b128 v[224:227], v188
	ds_read_b128 v[228:231], v189
	ds_read_b128 v[232:235], v222
	ds_read_b128 v[236:239], v223
	s_waitcnt lgkmcnt(4)
	v_mfma_f32_32x32x16_bf16 v[0:15], v[240:243], v[126:129], v[0:15]
	v_exp_f32_e32 v106, v106
	v_exp_f32_e32 v107, v107
	v_add_f32_e32 v180, v180, v96
	v_add_f32_e32 v180, v180, v97
	v_mfma_f32_32x32x16_bf16 v[16:31], v[130:133], v[126:129], v[16:31]
	v_exp_f32_e32 v108, v108
	v_exp_f32_e32 v109, v109
	v_add_f32_e32 v180, v180, v98
	v_add_f32_e32 v180, v180, v99
	v_mfma_f32_32x32x16_bf16 v[32:47], v[134:137], v[126:129], v[32:47]
	v_exp_f32_e32 v110, v110
	v_exp_f32_e32 v111, v111
	v_add_f32_e32 v180, v180, v100
	v_add_f32_e32 v180, v180, v101
	v_mfma_f32_32x32x16_bf16 v[48:63], v[184:187], v[126:129], v[48:63]
	v_exp_f32_e32 v112, v112
	v_exp_f32_e32 v113, v113
	v_add_f32_e32 v180, v180, v102
	v_add_f32_e32 v180, v180, v103
	ds_read_b128 v[240:243], v188 offset:4096
	ds_read_b128 v[130:133], v189 offset:4096
	ds_read_b128 v[134:137], v222 offset:4096
	ds_read_b128 v[184:187], v223 offset:4096
	s_waitcnt lgkmcnt(4)
	v_mfma_f32_32x32x16_bf16 v[82:97], v[224:227], v[150:153], v[64:79]
	v_add_f32_e32 v180, v180, v104
	v_add_f32_e32 v180, v180, v105
	v_add_f32_e32 v180, v180, v106
	v_cvt_pk_bf16_f32 v122, v98, v99
	v_cvt_pk_bf16_f32 v123, v100, v101
	s_add_i32 m0, s13, s68
	s_nop 0
	global_load_lds_dwordx4 v154, s[14:15]
	v_mfma_f32_32x32x16_bf16 v[82:97], v[228:231], v[146:149], v[82:97]
	v_add_f32_e32 v180, v180, v107
	v_add_f32_e32 v180, v180, v108
	v_add_f32_e32 v180, v180, v109
	v_cvt_pk_bf16_f32 v124, v102, v103
	v_cvt_pk_bf16_f32 v125, v104, v105
	s_add_i32 m0, s17, s69
	s_nop 0
	global_load_lds_dwordx4 v155, s[18:19]
	v_mfma_f32_32x32x16_bf16 v[82:97], v[232:235], v[142:145], v[82:97]
	v_add_f32_e32 v180, v180, v110
	v_add_f32_e32 v180, v180, v111
	v_cvt_pk_bf16_f32 v126, v106, v107
	v_cvt_pk_bf16_f32 v127, v108, v109
	s_add_i32 m0, m0, 0x400
	s_nop 0
	global_load_lds_dwordx4 v156, s[18:19]
	v_mfma_f32_32x32x16_bf16 v[82:97], v[236:239], v[138:141], v[82:97]
	v_add_f32_e32 v180, v180, v112
	v_add_f32_e32 v180, v180, v113
	v_cvt_pk_bf16_f32 v128, v110, v111
	v_cvt_pk_bf16_f32 v129, v112, v113
	v_cmp_ngt_f32_e32 vcc, s23, v180
	s_add_i32 s12, s12, 8192
	s_cmp_eq_u32 s12, 32768
	s_cselect_b32 s12, 0, s12
	s_add_i32 s84, s84, 16384
	s_cmp_eq_u32 s84, 114688
	s_cselect_b32 s84, 32768, s84
	s_waitcnt lgkmcnt(0)
	v_mfma_f32_32x32x16_bf16 v[98:113], v[240:243], v[150:153], v[64:79]
	v_add_u32_e32 v215, s84, v161
	v_add_u32_e32 v165, s84, v162
	v_add_u32_e32 v216, s84, v163
	v_add_u32_e32 v217, s84, v164
	ds_read_b64_tr_b16 v[224:225], v215 offset:0
	ds_read_b64_tr_b16 v[226:227], v215 offset:2048
	s_add_i32 s13, s13, 8192
	s_cmp_eq_u32 s13, 32768
	s_cselect_b32 s13, 0, s13
	v_mfma_f32_32x32x16_bf16 v[98:113], v[130:133], v[146:149], v[98:113]
	ds_read_b64_tr_b16 v[228:229], v165 offset:0
	ds_read_b64_tr_b16 v[230:231], v165 offset:2048
	ds_read_b64_tr_b16 v[232:233], v216 offset:0
	ds_read_b64_tr_b16 v[234:235], v216 offset:2048
	s_add_i32 s17, s17, 16384
	s_cmp_eq_u32 s17, 114688
	s_cselect_b32 s17, 32768, s17
	v_mfma_f32_32x32x16_bf16 v[98:113], v[134:137], v[142:145], v[98:113]
	ds_read_b64_tr_b16 v[236:237], v217 offset:0
	ds_read_b64_tr_b16 v[238:239], v217 offset:2048
	s_add_i32 s85, s85, 1
	s_cmp_lt_u32 s85, s6
	s_cselect_b32 s8, 0x40000, 0
	v_mfma_f32_32x32x16_bf16 v[98:113], v[184:187], v[138:141], v[98:113]
	s_add_u32 s14, s14, s8
	s_addc_u32 s15, s15, 0
	s_add_u32 s18, s18, s8
	s_addc_u32 s19, s19, 0
	ds_read_b64_tr_b16 v[240:241], v215 offset:4096
	ds_read_b64_tr_b16 v[242:243], v215 offset:6144
	ds_read_b64_tr_b16 v[130:131], v165 offset:4096
	ds_read_b64_tr_b16 v[132:133], v165 offset:6144
	ds_read_b64_tr_b16 v[134:135], v216 offset:4096
	ds_read_b64_tr_b16 v[136:137], v216 offset:6144
	ds_read_b64_tr_b16 v[184:185], v217 offset:4096
	ds_read_b64_tr_b16 v[186:187], v217 offset:6144
	s_cbranch_vccz .Lat_norescale_9
	ds_bpermute_b32 v182, v214, v180
	s_waitcnt lgkmcnt(0)
	v_add_f32_e32 v182, v180, v182
	v_min_f32_e32 v182, 0x7f61b1e6, v182
	v_log_f32_e32 v182, v182
	s_nop 0
	v_floor_f32_e32 v182, v182
	v_max_f32_e32 v182, 0, v182
	v_exp_f32_e64 v183, -v182
	v_add_f32_e32 v80, v80, v182
	v_mul_f32_e32 v81, v81, v183
	v_mul_f32_e32 v180, v180, v183
	v_xor_b32_e32 v64, 0x80000000, v80
	v_mov_b32_e32 v65, v64
	v_mov_b32_e32 v66, v64
	v_mov_b32_e32 v67, v64
	v_mov_b32_e32 v68, v64
	v_mov_b32_e32 v69, v64
	v_mov_b32_e32 v70, v64
	v_mov_b32_e32 v71, v64
	v_mov_b32_e32 v72, v64
	v_mov_b32_e32 v73, v64
	v_mov_b32_e32 v74, v64
	v_mov_b32_e32 v75, v64
	v_mov_b32_e32 v76, v64
	v_mov_b32_e32 v77, v64
	v_mov_b32_e32 v78, v64
	v_mov_b32_e32 v79, v64
	v_sub_f32_e32 v82, v82, v182
	v_sub_f32_e32 v83, v83, v182
	v_sub_f32_e32 v84, v84, v182
	v_sub_f32_e32 v85, v85, v182
	v_sub_f32_e32 v86, v86, v182
	v_sub_f32_e32 v87, v87, v182
	v_sub_f32_e32 v88, v88, v182
	v_sub_f32_e32 v89, v89, v182
	v_sub_f32_e32 v90, v90, v182
	v_sub_f32_e32 v91, v91, v182
	v_sub_f32_e32 v92, v92, v182
	v_sub_f32_e32 v93, v93, v182
	v_sub_f32_e32 v94, v94, v182
	v_sub_f32_e32 v95, v95, v182
	v_sub_f32_e32 v96, v96, v182
	v_sub_f32_e32 v97, v97, v182
	v_sub_f32_e32 v98, v98, v182
	v_sub_f32_e32 v99, v99, v182
	v_sub_f32_e32 v100, v100, v182
	v_sub_f32_e32 v101, v101, v182
	v_sub_f32_e32 v102, v102, v182
	v_sub_f32_e32 v103, v103, v182
	v_sub_f32_e32 v104, v104, v182
	v_sub_f32_e32 v105, v105, v182
	v_sub_f32_e32 v106, v106, v182
	v_sub_f32_e32 v107, v107, v182
	v_sub_f32_e32 v108, v108, v182
	v_sub_f32_e32 v109, v109, v182
	v_sub_f32_e32 v110, v110, v182
	v_sub_f32_e32 v111, v111, v182
	v_sub_f32_e32 v112, v112, v182
	v_sub_f32_e32 v113, v113, v182
	v_mul_f32_e32 v0, v0, v183
	v_mul_f32_e32 v1, v1, v183
	v_mul_f32_e32 v2, v2, v183
	v_mul_f32_e32 v3, v3, v183
	v_mul_f32_e32 v4, v4, v183
	v_mul_f32_e32 v5, v5, v183
	v_mul_f32_e32 v6, v6, v183
	v_mul_f32_e32 v7, v7, v183
	v_mul_f32_e32 v8, v8, v183
	v_mul_f32_e32 v9, v9, v183
	v_mul_f32_e32 v10, v10, v183
	v_mul_f32_e32 v11, v11, v183
	v_mul_f32_e32 v12, v12, v183
	v_mul_f32_e32 v13, v13, v183
	v_mul_f32_e32 v14, v14, v183
	v_mul_f32_e32 v15, v15, v183
	v_mul_f32_e32 v16, v16, v183
	v_mul_f32_e32 v17, v17, v183
	v_mul_f32_e32 v18, v18, v183
	v_mul_f32_e32 v19, v19, v183
	v_mul_f32_e32 v20, v20, v183
	v_mul_f32_e32 v21, v21, v183
	v_mul_f32_e32 v22, v22, v183
	v_mul_f32_e32 v23, v23, v183
	v_mul_f32_e32 v24, v24, v183
	v_mul_f32_e32 v25, v25, v183
	v_mul_f32_e32 v26, v26, v183
	v_mul_f32_e32 v27, v27, v183
	v_mul_f32_e32 v28, v28, v183
	v_mul_f32_e32 v29, v29, v183
	v_mul_f32_e32 v30, v30, v183
	v_mul_f32_e32 v31, v31, v183
	v_mul_f32_e32 v32, v32, v183
	v_mul_f32_e32 v33, v33, v183
	v_mul_f32_e32 v34, v34, v183
	v_mul_f32_e32 v35, v35, v183
	v_mul_f32_e32 v36, v36, v183
	v_mul_f32_e32 v37, v37, v183
	v_mul_f32_e32 v38, v38, v183
	v_mul_f32_e32 v39, v39, v183
	v_mul_f32_e32 v40, v40, v183
	v_mul_f32_e32 v41, v41, v183
	v_mul_f32_e32 v42, v42, v183
	v_mul_f32_e32 v43, v43, v183
	v_mul_f32_e32 v44, v44, v183
	v_mul_f32_e32 v45, v45, v183
	v_mul_f32_e32 v46, v46, v183
	v_mul_f32_e32 v47, v47, v183
	v_mul_f32_e32 v48, v48, v183
	v_mul_f32_e32 v49, v49, v183
	v_mul_f32_e32 v50, v50, v183
	v_mul_f32_e32 v51, v51, v183
	v_mul_f32_e32 v52, v52, v183
	v_mul_f32_e32 v53, v53, v183
	v_mul_f32_e32 v54, v54, v183
	v_mul_f32_e32 v55, v55, v183
	v_mul_f32_e32 v56, v56, v183
	v_mul_f32_e32 v57, v57, v183
	v_mul_f32_e32 v58, v58, v183
	v_mul_f32_e32 v59, v59, v183
	v_mul_f32_e32 v60, v60, v183
	v_mul_f32_e32 v61, v61, v183
	v_mul_f32_e32 v62, v62, v183
	v_mul_f32_e32 v63, v63, v183
	v_lshlrev_b32_e32 v181, 16, v114
	v_and_b32_e32 v114, 0xffff0000, v114
	v_mul_f32_e32 v181, v181, v183
	v_mul_f32_e32 v114, v114, v183
	v_cvt_pk_bf16_f32 v114, v181, v114
	v_lshlrev_b32_e32 v181, 16, v115
	v_and_b32_e32 v115, 0xffff0000, v115
	v_mul_f32_e32 v181, v181, v183
	v_mul_f32_e32 v115, v115, v183
	v_cvt_pk_bf16_f32 v115, v181, v115
	v_lshlrev_b32_e32 v181, 16, v116
	v_and_b32_e32 v116, 0xffff0000, v116
	v_mul_f32_e32 v181, v181, v183
	v_mul_f32_e32 v116, v116, v183
	v_cvt_pk_bf16_f32 v116, v181, v116
	v_lshlrev_b32_e32 v181, 16, v117
	v_and_b32_e32 v117, 0xffff0000, v117
	v_mul_f32_e32 v181, v181, v183
	v_mul_f32_e32 v117, v117, v183
	v_cvt_pk_bf16_f32 v117, v181, v117
	v_lshlrev_b32_e32 v181, 16, v118
	v_and_b32_e32 v118, 0xffff0000, v118
	v_mul_f32_e32 v181, v181, v183
	v_mul_f32_e32 v118, v118, v183
	v_cvt_pk_bf16_f32 v118, v181, v118
	v_lshlrev_b32_e32 v181, 16, v119
	v_and_b32_e32 v119, 0xffff0000, v119
	v_mul_f32_e32 v181, v181, v183
	v_mul_f32_e32 v119, v119, v183
	v_cvt_pk_bf16_f32 v119, v181, v119
	v_lshlrev_b32_e32 v181, 16, v120
	v_and_b32_e32 v120, 0xffff0000, v120
	v_mul_f32_e32 v181, v181, v183
	v_mul_f32_e32 v120, v120, v183
	v_cvt_pk_bf16_f32 v120, v181, v120
	v_lshlrev_b32_e32 v181, 16, v121
	v_and_b32_e32 v121, 0xffff0000, v121
	v_mul_f32_e32 v181, v181, v183
	v_mul_f32_e32 v121, v121, v183
	v_cvt_pk_bf16_f32 v121, v181, v121
	v_lshlrev_b32_e32 v181, 16, v122
	v_and_b32_e32 v122, 0xffff0000, v122
	v_mul_f32_e32 v181, v181, v183
	v_mul_f32_e32 v122, v122, v183
	v_cvt_pk_bf16_f32 v122, v181, v122
	v_lshlrev_b32_e32 v181, 16, v123
	v_and_b32_e32 v123, 0xffff0000, v123
	v_mul_f32_e32 v181, v181, v183
	v_mul_f32_e32 v123, v123, v183
	v_cvt_pk_bf16_f32 v123, v181, v123
	v_lshlrev_b32_e32 v181, 16, v124
	v_and_b32_e32 v124, 0xffff0000, v124
	v_mul_f32_e32 v181, v181, v183
	v_mul_f32_e32 v124, v124, v183
	v_cvt_pk_bf16_f32 v124, v181, v124
	v_lshlrev_b32_e32 v181, 16, v125
	v_and_b32_e32 v125, 0xffff0000, v125
	v_mul_f32_e32 v181, v181, v183
	v_mul_f32_e32 v125, v125, v183
	v_cvt_pk_bf16_f32 v125, v181, v125
	v_lshlrev_b32_e32 v181, 16, v126
	v_and_b32_e32 v126, 0xffff0000, v126
	v_mul_f32_e32 v181, v181, v183
	v_mul_f32_e32 v126, v126, v183
	v_cvt_pk_bf16_f32 v126, v181, v126
	v_lshlrev_b32_e32 v181, 16, v127
	v_and_b32_e32 v127, 0xffff0000, v127
	v_mul_f32_e32 v181, v181, v183
	v_mul_f32_e32 v127, v127, v183
	v_cvt_pk_bf16_f32 v127, v181, v127
	v_lshlrev_b32_e32 v181, 16, v128
	v_and_b32_e32 v128, 0xffff0000, v128
	v_mul_f32_e32 v181, v181, v183
	v_mul_f32_e32 v128, v128, v183
	v_cvt_pk_bf16_f32 v128, v181, v128
	v_lshlrev_b32_e32 v181, 16, v129
	v_and_b32_e32 v129, 0xffff0000, v129
	v_mul_f32_e32 v181, v181, v183
	v_mul_f32_e32 v129, v129, v183
	v_cvt_pk_bf16_f32 v129, v181, v129
.Lat_norescale_9:
	v_add_f32_e32 v81, v81, v180
	s_add_i32 s5, s5, 1
	s_waitcnt vmcnt(3) lgkmcnt(15)
	s_barrier
	s_cmp_lt_u32 s5, s6
	s_cbranch_scc1 .Lat_loop
	s_branch .Lat_loopexit
.Lat_rare_8:
	s_add_i32 s16, s81, 1
	s_cmp_gt_i32 s5, s16
	s_cbranch_scc1 .Lat_noqk_3
	s_cmp_gt_i32 s5, s81
	s_cbranch_scc1 .Lat_pvonly_6
	s_waitcnt lgkmcnt(14)
	v_mfma_f32_32x32x16_bf16 v[0:15], v[224:227], v[114:117], v[0:15]
	v_exp_f32_e32 v82, v82
	v_exp_f32_e32 v83, v83
	v_mov_b32_e32 v180, 0
	ds_read_b64_tr_b16 v[224:225], v215 offset:8192
	ds_read_b64_tr_b16 v[226:227], v215 offset:10240
	s_waitcnt lgkmcnt(14)
	v_mfma_f32_32x32x16_bf16 v[16:31], v[228:231], v[114:117], v[16:31]
	v_exp_f32_e32 v84, v84
	v_exp_f32_e32 v85, v85
	v_add_f32_e32 v180, v180, v82
	v_add_f32_e32 v180, v180, v83
	ds_read_b64_tr_b16 v[228:229], v165 offset:8192
	ds_read_b64_tr_b16 v[230:231], v165 offset:10240
	s_waitcnt lgkmcnt(14)
	v_mfma_f32_32x32x16_bf16 v[32:47], v[232:235], v[114:117], v[32:47]
	v_exp_f32_e32 v86, v86
	v_exp_f32_e32 v87, v87
	v_add_f32_e32 v180, v180, v84
	v_add_f32_e32 v180, v180, v85
	ds_read_b64_tr_b16 v[232:233], v216 offset:8192
	ds_read_b64_tr_b16 v[234:235], v216 offset:10240
	s_waitcnt lgkmcnt(14)
	v_mfma_f32_32x32x16_bf16 v[48:63], v[236:239], v[114:117], v[48:63]
	v_exp_f32_e32 v88, v88
	v_exp_f32_e32 v89, v89
	v_add_f32_e32 v180, v180, v86
	v_add_f32_e32 v180, v180, v87
	ds_read_b64_tr_b16 v[236:237], v217 offset:8192
	ds_read_b64_tr_b16 v[238:239], v217 offset:10240
	s_waitcnt lgkmcnt(14)
	v_mfma_f32_32x32x16_bf16 v[0:15], v[240:243], v[118:121], v[0:15]
	v_exp_f32_e32 v90, v90
	v_exp_f32_e32 v91, v91
	v_add_f32_e32 v180, v180, v88
	v_add_f32_e32 v180, v180, v89
	v_cvt_pk_bf16_f32 v114, v82, v83
	ds_read_b64_tr_b16 v[240:241], v215 offset:12288
	ds_read_b64_tr_b16 v[242:243], v215 offset:14336
	s_waitcnt lgkmcnt(14)
	v_mfma_f32_32x32x16_bf16 v[16:31], v[130:133], v[118:121], v[16:31]
	v_exp_f32_e32 v92, v92
	v_exp_f32_e32 v93, v93
	v_add_f32_e32 v180, v180, v90
	v_add_f32_e32 v180, v180, v91
	v_cvt_pk_bf16_f32 v115, v84, v85
	ds_read_b64_tr_b16 v[130:131], v165 offset:12288
	ds_read_b64_tr_b16 v[132:133], v165 offset:14336
	s_waitcnt lgkmcnt(14)
	v_mfma_f32_32x32x16_bf16 v[32:47], v[134:137], v[118:121], v[32:47]
	v_exp_f32_e32 v94, v94
	v_exp_f32_e32 v95, v95
	v_add_f32_e32 v180, v180, v92
	v_add_f32_e32 v180, v180, v93
	v_cvt_pk_bf16_f32 v116, v86, v87
	ds_read_b64_tr_b16 v[134:135], v216 offset:12288
	ds_read_b64_tr_b16 v[136:137], v216 offset:14336
	s_waitcnt lgkmcnt(14)
	v_mfma_f32_32x32x16_bf16 v[48:63], v[184:187], v[118:121], v[48:63]
	v_exp_f32_e32 v96, v96
	v_exp_f32_e32 v97, v97
	v_add_f32_e32 v180, v180, v94
	v_add_f32_e32 v180, v180, v95
	v_cvt_pk_bf16_f32 v117, v88, v89
	ds_read_b64_tr_b16 v[184:185], v217 offset:12288
	ds_read_b64_tr_b16 v[186:187], v217 offset:14336
	s_waitcnt lgkmcnt(14)
	v_mfma_f32_32x32x16_bf16 v[0:15], v[224:227], v[122:125], v[0:15]
	v_exp_f32_e32 v98, v98
	v_exp_f32_e32 v99, v99
	v_add_f32_e32 v180, v180, v96
	v_add_f32_e32 v180, v180, v97
	v_cvt_pk_bf16_f32 v118, v90, v91
	s_waitcnt lgkmcnt(12)
	v_mfma_f32_32x32x16_bf16 v[16:31], v[228:231], v[122:125], v[16:31]
	v_exp_f32_e32 v100, v100
	v_exp_f32_e32 v101, v101
	v_add_f32_e32 v180, v180, v98
	v_add_f32_e32 v180, v180, v99
	v_cvt_pk_bf16_f32 v119, v92, v93
	s_waitcnt lgkmcnt(10)
	v_mfma_f32_32x32x16_bf16 v[32:47], v[232:235], v[122:125], v[32:47]
	v_exp_f32_e32 v102, v102
	v_exp_f32_e32 v103, v103
	v_add_f32_e32 v180, v180, v100
	v_add_f32_e32 v180, v180, v101
	v_cvt_pk_bf16_f32 v120, v94, v95
	s_waitcnt lgkmcnt(8)
	v_mfma_f32_32x32x16_bf16 v[48:63], v[236:239], v[122:125], v[48:63]
	v_exp_f32_e32 v104, v104
	v_exp_f32_e32 v105, v105
	v_add_f32_e32 v180, v180, v102
	v_add_f32_e32 v180, v180, v103
	v_cvt_pk_bf16_f32 v121, v96, v97
	ds_read_b128 v[224:227], v188
	ds_read_b128 v[228:231], v189
	ds_read_b128 v[232:235], v222
	ds_read_b128 v[236:239], v223
	s_waitcnt lgkmcnt(10)
	v_mfma_f32_32x32x16_bf16 v[0:15], v[240:243], v[126:129], v[0:15]
	v_exp_f32_e32 v106, v106
	v_exp_f32_e32 v107, v107
	v_add_f32_e32 v180, v180, v104
	v_add_f32_e32 v180, v180, v105
	v_cvt_pk_bf16_f32 v122, v98, v99
	s_waitcnt lgkmcnt(8)
	v_mfma_f32_32x32x16_bf16 v[16:31], v[130:133], v[126:129], v[16:31]
	v_exp_f32_e32 v108, v108
	v_exp_f32_e32 v109, v109
	v_add_f32_e32 v180, v180, v106
	v_add_f32_e32 v180, v180, v107
	v_cvt_pk_bf16_f32 v123, v100, v101
	s_waitcnt lgkmcnt(6)
	v_mfma_f32_32x32x16_bf16 v[32:47], v[134:137], v[126:129], v[32:47]
	v_exp_f32_e32 v110, v110
	v_exp_f32_e32 v111, v111
	v_add_f32_e32 v180, v180, v108
	v_add_f32_e32 v180, v180, v109
	v_cvt_pk_bf16_f32 v124, v102, v103
	s_waitcnt lgkmcnt(4)
	v_mfma_f32_32x32x16_bf16 v[48:63], v[184:187], v[126:129], v[48:63]
	v_exp_f32_e32 v112, v112
	v_exp_f32_e32 v113, v113
	v_add_f32_e32 v180, v180, v110
	v_add_f32_e32 v180, v180, v111
	v_cvt_pk_bf16_f32 v125, v104, v105
	s_nop 0
	v_add_f32_e32 v180, v180, v112
	v_add_f32_e32 v180, v180, v113
	v_cvt_pk_bf16_f32 v126, v106, v107
	v_cvt_pk_bf16_f32 v127, v108, v109
	v_cvt_pk_bf16_f32 v128, v110, v111
	v_cvt_pk_bf16_f32 v129, v112, v113
	v_cmp_ngt_f32_e32 vcc, s23, v180
	s_cbranch_vccz .Lat_norescale_10
	ds_bpermute_b32 v182, v214, v180
	s_waitcnt lgkmcnt(0)
	v_add_f32_e32 v182, v180, v182
	v_min_f32_e32 v182, 0x7f61b1e6, v182
	v_log_f32_e32 v182, v182
	s_nop 0
	v_floor_f32_e32 v182, v182
	v_max_f32_e32 v182, 0, v182
	v_exp_f32_e64 v183, -v182
	v_add_f32_e32 v80, v80, v182
	v_mul_f32_e32 v81, v81, v183
	v_mul_f32_e32 v180, v180, v183
	v_xor_b32_e32 v64, 0x80000000, v80
	v_mov_b32_e32 v65, v64
	v_mov_b32_e32 v66, v64
	v_mov_b32_e32 v67, v64
	v_mov_b32_e32 v68, v64
	v_mov_b32_e32 v69, v64
	v_mov_b32_e32 v70, v64
	v_mov_b32_e32 v71, v64
	v_mov_b32_e32 v72, v64
	v_mov_b32_e32 v73, v64
	v_mov_b32_e32 v74, v64
	v_mov_b32_e32 v75, v64
	v_mov_b32_e32 v76, v64
	v_mov_b32_e32 v77, v64
	v_mov_b32_e32 v78, v64
	v_mov_b32_e32 v79, v64
	v_mul_f32_e32 v82, v82, v183
	v_mul_f32_e32 v83, v83, v183
	v_mul_f32_e32 v84, v84, v183
	v_mul_f32_e32 v85, v85, v183
	v_mul_f32_e32 v86, v86, v183
	v_mul_f32_e32 v87, v87, v183
	v_mul_f32_e32 v88, v88, v183
	v_mul_f32_e32 v89, v89, v183
	v_mul_f32_e32 v90, v90, v183
	v_mul_f32_e32 v91, v91, v183
	v_mul_f32_e32 v92, v92, v183
	v_mul_f32_e32 v93, v93, v183
	v_mul_f32_e32 v94, v94, v183
	v_mul_f32_e32 v95, v95, v183
	v_mul_f32_e32 v96, v96, v183
	v_mul_f32_e32 v97, v97, v183
	v_mul_f32_e32 v98, v98, v183
	v_mul_f32_e32 v99, v99, v183
	v_mul_f32_e32 v100, v100, v183
	v_mul_f32_e32 v101, v101, v183
	v_mul_f32_e32 v102, v102, v183
	v_mul_f32_e32 v103, v103, v183
	v_mul_f32_e32 v104, v104, v183
	v_mul_f32_e32 v105, v105, v183
	v_mul_f32_e32 v106, v106, v183
	v_mul_f32_e32 v107, v107, v183
	v_mul_f32_e32 v108, v108, v183
	v_mul_f32_e32 v109, v109, v183
	v_mul_f32_e32 v110, v110, v183
	v_mul_f32_e32 v111, v111, v183
	v_mul_f32_e32 v112, v112, v183
	v_mul_f32_e32 v113, v113, v183
	v_mul_f32_e32 v0, v0, v183
	v_mul_f32_e32 v1, v1, v183
	v_mul_f32_e32 v2, v2, v183
	v_mul_f32_e32 v3, v3, v183
	v_mul_f32_e32 v4, v4, v183
	v_mul_f32_e32 v5, v5, v183
	v_mul_f32_e32 v6, v6, v183
	v_mul_f32_e32 v7, v7, v183
	v_mul_f32_e32 v8, v8, v183
	v_mul_f32_e32 v9, v9, v183
	v_mul_f32_e32 v10, v10, v183
	v_mul_f32_e32 v11, v11, v183
	v_mul_f32_e32 v12, v12, v183
	v_mul_f32_e32 v13, v13, v183
	v_mul_f32_e32 v14, v14, v183
	v_mul_f32_e32 v15, v15, v183
	v_mul_f32_e32 v16, v16, v183
	v_mul_f32_e32 v17, v17, v183
	v_mul_f32_e32 v18, v18, v183
	v_mul_f32_e32 v19, v19, v183
	v_mul_f32_e32 v20, v20, v183
	v_mul_f32_e32 v21, v21, v183
	v_mul_f32_e32 v22, v22, v183
	v_mul_f32_e32 v23, v23, v183
	v_mul_f32_e32 v24, v24, v183
	v_mul_f32_e32 v25, v25, v183
	v_mul_f32_e32 v26, v26, v183
	v_mul_f32_e32 v27, v27, v183
	v_mul_f32_e32 v28, v28, v183
	v_mul_f32_e32 v29, v29, v183
	v_mul_f32_e32 v30, v30, v183
	v_mul_f32_e32 v31, v31, v183
	v_mul_f32_e32 v32, v32, v183
	v_mul_f32_e32 v33, v33, v183
	v_mul_f32_e32 v34, v34, v183
	v_mul_f32_e32 v35, v35, v183
	v_mul_f32_e32 v36, v36, v183
	v_mul_f32_e32 v37, v37, v183
	v_mul_f32_e32 v38, v38, v183
	v_mul_f32_e32 v39, v39, v183
	v_mul_f32_e32 v40, v40, v183
	v_mul_f32_e32 v41, v41, v183
	v_mul_f32_e32 v42, v42, v183
	v_mul_f32_e32 v43, v43, v183
	v_mul_f32_e32 v44, v44, v183
	v_mul_f32_e32 v45, v45, v183
	v_mul_f32_e32 v46, v46, v183
	v_mul_f32_e32 v47, v47, v183
	v_mul_f32_e32 v48, v48, v183
	v_mul_f32_e32 v49, v49, v183
	v_mul_f32_e32 v50, v50, v183
	v_mul_f32_e32 v51, v51, v183
	v_mul_f32_e32 v52, v52, v183
	v_mul_f32_e32 v53, v53, v183
	v_mul_f32_e32 v54, v54, v183
	v_mul_f32_e32 v55, v55, v183
	v_mul_f32_e32 v56, v56, v183
	v_mul_f32_e32 v57, v57, v183
	v_mul_f32_e32 v58, v58, v183
	v_mul_f32_e32 v59, v59, v183
	v_mul_f32_e32 v60, v60, v183
	v_mul_f32_e32 v61, v61, v183
	v_mul_f32_e32 v62, v62, v183
	v_mul_f32_e32 v63, v63, v183
	v_cvt_pk_bf16_f32 v114, v82, v83
	v_cvt_pk_bf16_f32 v115, v84, v85
	v_cvt_pk_bf16_f32 v116, v86, v87
	v_cvt_pk_bf16_f32 v117, v88, v89
	v_cvt_pk_bf16_f32 v118, v90, v91
	v_cvt_pk_bf16_f32 v119, v92, v93
	v_cvt_pk_bf16_f32 v120, v94, v95
	v_cvt_pk_bf16_f32 v121, v96, v97
	v_cvt_pk_bf16_f32 v122, v98, v99
	v_cvt_pk_bf16_f32 v123, v100, v101
	v_cvt_pk_bf16_f32 v124, v102, v103
	v_cvt_pk_bf16_f32 v125, v104, v105
	v_cvt_pk_bf16_f32 v126, v106, v107
	v_cvt_pk_bf16_f32 v127, v108, v109
	v_cvt_pk_bf16_f32 v128, v110, v111
	v_cvt_pk_bf16_f32 v129, v112, v113

.Lat_loopexit:
	s_add_i32 s16, s81, 1
	s_cmp_gt_i32 s5, s16
	s_cbranch_scc1 .Lat_nolast_11
	s_waitcnt lgkmcnt(14)
	v_mfma_f32_32x32x16_bf16 v[0:15], v[224:227], v[114:117], v[0:15]
	ds_read_b64_tr_b16 v[224:225], v215 offset:8192
	ds_read_b64_tr_b16 v[226:227], v215 offset:10240
	s_waitcnt lgkmcnt(14)
	v_mfma_f32_32x32x16_bf16 v[16:31], v[228:231], v[114:117], v[16:31]
	ds_read_b64_tr_b16 v[228:229], v165 offset:8192
	ds_read_b64_tr_b16 v[230:231], v165 offset:10240
	s_waitcnt lgkmcnt(14)
	v_mfma_f32_32x32x16_bf16 v[32:47], v[232:235], v[114:117], v[32:47]
	ds_read_b64_tr_b16 v[232:233], v216 offset:8192
	ds_read_b64_tr_b16 v[234:235], v216 offset:10240
	s_waitcnt lgkmcnt(14)
	v_mfma_f32_32x32x16_bf16 v[48:63], v[236:239], v[114:117], v[48:63]
	ds_read_b64_tr_b16 v[236:237], v217 offset:8192
	ds_read_b64_tr_b16 v[238:239], v217 offset:10240
	s_waitcnt lgkmcnt(14)
	v_mfma_f32_32x32x16_bf16 v[0:15], v[240:243], v[118:121], v[0:15]
	ds_read_b64_tr_b16 v[240:241], v215 offset:12288
	ds_read_b64_tr_b16 v[242:243], v215 offset:14336
	s_waitcnt lgkmcnt(14)
	v_mfma_f32_32x32x16_bf16 v[16:31], v[130:133], v[118:121], v[16:31]
	ds_read_b64_tr_b16 v[130:131], v165 offset:12288
	ds_read_b64_tr_b16 v[132:133], v165 offset:14336
	s_waitcnt lgkmcnt(14)
	v_mfma_f32_32x32x16_bf16 v[32:47], v[134:137], v[118:121], v[32:47]
	ds_read_b64_tr_b16 v[134:135], v216 offset:12288
	ds_read_b64_tr_b16 v[136:137], v216 offset:14336
	s_waitcnt lgkmcnt(14)
	v_mfma_f32_32x32x16_bf16 v[48:63], v[184:187], v[118:121], v[48:63]
	ds_read_b64_tr_b16 v[184:185], v217 offset:12288
	ds_read_b64_tr_b16 v[186:187], v217 offset:14336
	s_waitcnt lgkmcnt(14)
	v_mfma_f32_32x32x16_bf16 v[0:15], v[224:227], v[122:125], v[0:15]
	s_waitcnt lgkmcnt(12)
	v_mfma_f32_32x32x16_bf16 v[16:31], v[228:231], v[122:125], v[16:31]
	s_waitcnt lgkmcnt(10)
	v_mfma_f32_32x32x16_bf16 v[32:47], v[232:235], v[122:125], v[32:47]
	s_waitcnt lgkmcnt(8)
	v_mfma_f32_32x32x16_bf16 v[48:63], v[236:239], v[122:125], v[48:63]
	s_waitcnt lgkmcnt(6)
	v_mfma_f32_32x32x16_bf16 v[0:15], v[240:243], v[126:129], v[0:15]
	s_waitcnt lgkmcnt(4)
	v_mfma_f32_32x32x16_bf16 v[16:31], v[130:133], v[126:129], v[16:31]
	s_waitcnt lgkmcnt(2)
	v_mfma_f32_32x32x16_bf16 v[32:47], v[134:137], v[126:129], v[32:47]
	s_waitcnt lgkmcnt(0)
	v_mfma_f32_32x32x16_bf16 v[48:63], v[184:187], v[126:129], v[48:63]
